# XCD-parity stagger (odd blockIdx waits ~9us) at the start of the phase-1 GEMM job so half-chip epilogue store bursts overlap the other half's K-loops
# speedup vs baseline: 1.0649x; 1.0037x over previous
; #define PG8_STAGE(bufoff, gbase, voff) do { _Pragma("unroll") for (int _i = 0; _i < 2; ++_i) \
;         __builtin_amdgcn_global_load_lds((const unsigned*)((const char*)(gbase) + (voff)[_i]), (LAS unsigned*)(lds + (bufoff) + ldsw + _i * 8192), 16, 0, 0); } while (0)
; #define PG8_WAIT_V(n) asm volatile("s_waitcnt vmcnt(" #n ")" ::: "memory")
; #define PG8_BAR __builtin_amdgcn_s_barrier()
; __device__ __forceinline__ void gemm_phase(LAS unsigned char* lds, CParams& p, const Job& jb) {
;     ...
;     const char* cA = cur.A; const char* cB = cur.B;
;     PG8_STAGE(PG8_SB(0, 0), cB, voffB); PG8_STAGE(PG8_SA(0, 0), cA, voffA); PG8_STAGE(PG8_SB(0, 1), cB + hstepB, voffB); PG8_STAGE(PG8_SA(0, 1), cA + hstepA, voffA);
;     if (wr == 1) PG8_BAR;
;     PG8_WAIT_V(4); PG8_BAR;
;     PG8_STAGE(PG8_SB(1, 0), cB + kstep, voffB); PG8_STAGE(PG8_SA(1, 0), cA + kstep, voffA); PG8_STAGE(PG8_SB(1, 1), cB + hstepB + kstep, voffB);
;     PG8_WAIT_V(6); PG8_BAR;
;     for (;;) {
;         const bool has_next = S.next(ui + 1, nxt);
; __device__ __forceinline__ bool get_job(CParams& p, int ph, int j, Job& jb) {
;     ...
;     case 1: A = p.xn; B = p.WinT; jb.N = 6400; jb.kind = E_G1; jb.mode = 3; jb.A2 = (const char*)p.memn; jb.B2 = (const char*)p.WkvT; break;
.LBB0_515:
	s_cmp_lg_u32 s18, 0
	s_cbranch_scc1 .Lstag_done
	s_mov_b32 s100, 0
	s_cmp_eq_u32 s43, 1
	s_cselect_b32 s100, 3, s100
	s_bitcmp1_b32 s93, 0
	s_cselect_b32 s100, s100, 0
	s_cmp_eq_u32 s100, 0
	s_cbranch_scc1 .Lstag_done
.Lstag_loop:
	s_sleep 100
	s_sub_u32 s100, s100, 1
	s_cmp_lg_u32 s100, 0
	s_cbranch_scc1 .Lstag_loop

; __global__ void __launch_bounds__(512, 2) mega(Params p_unused) {
	.amdhsa_kernel _Z4mega6Params
		.amdhsa_group_segment_fixed_size 0
		.amdhsa_private_segment_fixed_size 0
		.amdhsa_kernarg_size 872
		.amdhsa_user_sgpr_count 2
		.amdhsa_user_sgpr_dispatch_ptr 0
		.amdhsa_user_sgpr_queue_ptr 0
		.amdhsa_user_sgpr_kernarg_segment_ptr 1
		.amdhsa_user_sgpr_dispatch_id 0
		.amdhsa_user_sgpr_kernarg_preload_length 0
		.amdhsa_user_sgpr_kernarg_preload_offset 0
		.amdhsa_user_sgpr_private_segment_size 0
		.amdhsa_uses_dynamic_stack 0
		.amdhsa_enable_private_segment 0
		.amdhsa_system_sgpr_workgroup_id_x 1
		.amdhsa_system_sgpr_workgroup_id_y 0
		.amdhsa_system_sgpr_workgroup_id_z 0
		.amdhsa_system_sgpr_workgroup_info 0
		.amdhsa_system_vgpr_workitem_id 2
		.amdhsa_next_free_vgpr 247
		.amdhsa_next_free_sgpr 102
		.amdhsa_accum_offset 248
		.amdhsa_reserve_vcc 1
		.amdhsa_float_round_mode_32 0
		.amdhsa_float_round_mode_16_64 0
		.amdhsa_float_denorm_mode_32 3
		.amdhsa_float_denorm_mode_16_64 3
		.amdhsa_dx10_clamp 1
		.amdhsa_ieee_mode 1
		.amdhsa_fp16_overflow 0
		.amdhsa_tg_split 0
		.amdhsa_exception_fp_ieee_invalid_op 0
		.amdhsa_exception_fp_denorm_src 0
		.amdhsa_exception_fp_ieee_div_zero 0
		.amdhsa_exception_fp_ieee_overflow 0
		.amdhsa_exception_fp_ieee_underflow 0
		.amdhsa_exception_fp_ieee_inexact 0
		.amdhsa_exception_int_div_zero 0
	.end_amdhsa_kernel

; __global__ void __launch_bounds__(512, 2) mega(Params p_unused) {
amdhsa.kernels:
  - .agpr_count:     0
    .args:
      - .offset:         0
        .size:           616
        .value_kind:     by_value
      - .offset:         616
        .size:           4
        .value_kind:     hidden_block_count_x
      - .offset:         620
        .size:           4
        .value_kind:     hidden_block_count_y
      - .offset:         624
        .size:           4
        .value_kind:     hidden_block_count_z
      - .offset:         628
        .size:           2
        .value_kind:     hidden_group_size_x
      - .offset:         630
        .size:           2
        .value_kind:     hidden_group_size_y
      - .offset:         632
        .size:           2
        .value_kind:     hidden_group_size_z
      - .offset:         634
        .size:           2
        .value_kind:     hidden_remainder_x
      - .offset:         636
        .size:           2
        .value_kind:     hidden_remainder_y
      - .offset:         638
        .size:           2
        .value_kind:     hidden_remainder_z
      - .offset:         656
        .size:           8
        .value_kind:     hidden_global_offset_x
      - .offset:         664
        .size:           8
        .value_kind:     hidden_global_offset_y
      - .offset:         672
        .size:           8
        .value_kind:     hidden_global_offset_z
      - .offset:         680
        .size:           2
        .value_kind:     hidden_grid_dims
      - .offset:         704
        .size:           8
        .value_kind:     hidden_multigrid_sync_arg
      - .offset:         736
        .size:           4
        .value_kind:     hidden_dynamic_lds_size
    .group_segment_fixed_size: 0
    .kernarg_segment_align: 8
    .kernarg_segment_size: 872
    .language:       OpenCL C
    .language_version:
      - 2
      - 0
    .max_flat_workgroup_size: 512
    .name:           _Z4mega6Params
    .private_segment_fixed_size: 0
    .sgpr_count:     108
    .sgpr_spill_count: 206
    .symbol:         _Z4mega6Params.kd
    .uniform_work_group_size: 1
    .uses_dynamic_stack: false
    .vgpr_count:     247
    .vgpr_spill_count: 0
    .wavefront_size: 64
